# attnC: QK in key-half-major order; first softmax group of the finished half (exp, mask, pack, row-sum) issued in the second half's MFMA shadows
# speedup vs baseline: 1.0119x; 1.0020x over previous
.LBB0_1057:
	v_cmp_le_i32_e32 vcc, s12, v187
	s_and_saveexec_b64 s[10:11], vcc
	s_cbranch_execz .LBB0_1059
	s_lshl_b32 s12, s12, 15
	s_and_b32 s12, s12, 0x8000
	s_add_i32 s12, s80, s12
	v_add3_u32 v220, s12, v186, v190
	v_add_u32_e32 v221, v220, v199
	v_add_u32_e32 v222, v220, v200
	v_add_u32_e32 v223, v220, v201
	v_add_u32_e32 v224, v220, v202
	v_add_u32_e32 v225, v220, v203
	v_add_u32_e32 v226, v220, v216
	v_add_u32_e32 v227, v220, v217
	v_add_u32_e32 v228, v220, v218
	v_lshrrev_b32_e32 v229, v189, v168
	v_lshrrev_b32_e32 v230, v189, v169
	v_add3_u32 v233, s12, v191, v188
	ds_read_b128 v[2:5], v233
	v_add3_u32 v233, s12, v192, v188
	ds_read_b128 v[8:11], v233
	v_add3_u32 v233, s12, v193, v188
	ds_read_b128 v[12:15], v233
	s_waitcnt lgkmcnt(2)
	v_mfma_f32_32x32x16_bf16 v[112:127], v[2:5], v[156:159], v[16:31]
	v_add3_u32 v233, s12, v194, v188
	ds_read_b128 v[2:5], v233
	s_waitcnt lgkmcnt(2)
	v_mfma_f32_32x32x16_bf16 v[112:127], v[8:11], v[128:131], v[112:127]
	v_add3_u32 v233, s12, v195, v188
	ds_read_b128 v[8:11], v233
	s_waitcnt lgkmcnt(2)
	v_mfma_f32_32x32x16_bf16 v[112:127], v[12:15], v[132:135], v[112:127]
	v_add3_u32 v233, s12, v196, v188
	ds_read_b128 v[12:15], v233
	s_waitcnt lgkmcnt(2)
	v_mfma_f32_32x32x16_bf16 v[112:127], v[2:5], v[136:139], v[112:127]
	v_add3_u32 v233, s12, v197, v188
	ds_read_b128 v[2:5], v233
	s_waitcnt lgkmcnt(2)
	v_mfma_f32_32x32x16_bf16 v[112:127], v[8:11], v[140:143], v[112:127]
	v_add3_u32 v233, s12, v198, v188
	ds_read_b128 v[8:11], v233
	s_waitcnt lgkmcnt(2)
	v_mfma_f32_32x32x16_bf16 v[112:127], v[12:15], v[144:147], v[112:127]
	v_add3_u32 v233, s12, v191, v188
	ds_read_b128 v[12:15], v233 offset:8192
	s_waitcnt lgkmcnt(2)
	v_mfma_f32_32x32x16_bf16 v[112:127], v[2:5], v[148:151], v[112:127]
	v_add3_u32 v233, s12, v192, v188
	ds_read_b128 v[2:5], v233 offset:8192
	s_waitcnt lgkmcnt(2)
	v_mfma_f32_32x32x16_bf16 v[112:127], v[8:11], v[152:155], v[112:127]
	v_add3_u32 v233, s12, v193, v188
	ds_read_b128 v[8:11], v233 offset:8192
	s_waitcnt lgkmcnt(2)
	v_mfma_f32_32x32x16_bf16 v[96:111], v[12:15], v[156:159], v[16:31]
	v_add3_u32 v233, s12, v194, v188
	ds_read_b128 v[12:15], v233 offset:8192
	s_waitcnt lgkmcnt(2)
	v_mfma_f32_32x32x16_bf16 v[96:111], v[2:5], v[128:131], v[96:111]
	v_exp_f32_e32 v112, v112
	v_exp_f32_e32 v113, v113
	v_exp_f32_e32 v114, v114
	v_exp_f32_e32 v115, v115
	v_add3_u32 v233, s12, v195, v188
	ds_read_b128 v[2:5], v233 offset:8192
	s_waitcnt lgkmcnt(2)
	v_mfma_f32_32x32x16_bf16 v[96:111], v[8:11], v[132:135], v[96:111]
	v_exp_f32_e32 v116, v116
	v_exp_f32_e32 v117, v117
	v_exp_f32_e32 v118, v118
	v_exp_f32_e32 v119, v119
	v_add3_u32 v233, s12, v196, v188
	ds_read_b128 v[8:11], v233 offset:8192
	s_waitcnt lgkmcnt(2)
	v_mfma_f32_32x32x16_bf16 v[96:111], v[12:15], v[136:139], v[96:111]
	v_bfe_i32 v231, v229, 0, 1
	v_and_b32_e32 v112, v112, v231
	v_bfe_i32 v232, v229, 1, 1
	v_and_b32_e32 v113, v113, v232
	v_bfe_i32 v231, v229, 2, 1
	v_and_b32_e32 v114, v114, v231
	v_bfe_i32 v232, v229, 3, 1
	v_and_b32_e32 v115, v115, v232
	v_add3_u32 v233, s12, v197, v188
	ds_read_b128 v[12:15], v233 offset:8192
	s_waitcnt lgkmcnt(2)
	v_mfma_f32_32x32x16_bf16 v[96:111], v[2:5], v[140:143], v[96:111]
	v_bfe_i32 v231, v229, 8, 1
	v_and_b32_e32 v116, v116, v231
	v_bfe_i32 v232, v229, 9, 1
	v_and_b32_e32 v117, v117, v232
	v_bfe_i32 v231, v229, 10, 1
	v_and_b32_e32 v118, v118, v231
	v_bfe_i32 v232, v229, 11, 1
	v_and_b32_e32 v119, v119, v232
	v_add3_u32 v233, s12, v198, v188
	ds_read_b128 v[2:5], v233 offset:8192
	s_waitcnt lgkmcnt(2)
	v_mfma_f32_32x32x16_bf16 v[96:111], v[8:11], v[144:147], v[96:111]
	v_cvt_pk_bf16_f32 v208, v112, v113
	v_cvt_pk_bf16_f32 v209, v114, v115
	v_add_f32_e32 v0, 0, v112
	v_add_f32_e32 v0, v113, v0
	v_add_f32_e32 v0, v114, v0
	s_waitcnt lgkmcnt(1)
	v_mfma_f32_32x32x16_bf16 v[96:111], v[12:15], v[148:151], v[96:111]
	v_cvt_pk_bf16_f32 v210, v116, v117
	v_cvt_pk_bf16_f32 v211, v118, v119
	v_add_f32_e32 v0, v115, v0
	v_add_f32_e32 v0, v116, v0
	v_add_f32_e32 v0, v117, v0
	s_waitcnt lgkmcnt(0)
	v_mfma_f32_32x32x16_bf16 v[96:111], v[2:5], v[152:155], v[96:111]
	v_add_f32_e32 v0, v118, v0
	v_add_f32_e32 v0, v119, v0
	ds_read_b64 v[8:9], v221 offset:16384
	ds_read_b64 v[10:11], v222 offset:16384
	ds_read_b64 v[12:13], v221 offset:20480
	ds_read_b64 v[14:15], v222 offset:20480
	ds_read_b64 v[236:237], v221 offset:28672
	ds_read_b64 v[238:239], v222 offset:28672
	ds_read_b64 v[240:241], v221 offset:24576
	ds_read_b64 v[242:243], v222 offset:24576
	ds_read_b64 v[244:245], v223 offset:16384
	ds_read_b64 v[246:247], v224 offset:16384
	s_waitcnt lgkmcnt(8)
	v_mfma_f32_32x32x16_bf16 v[80:95], v[8:11], v[208:211], v[80:95]
	ds_read_b64 v[112:113], v223 offset:20480
	ds_read_b64 v[114:115], v224 offset:20480
	v_exp_f32_e32 v120, v120
	v_exp_f32_e32 v121, v121
	s_waitcnt lgkmcnt(8)
	v_mfma_f32_32x32x16_bf16 v[64:79], v[12:15], v[208:211], v[64:79]
	ds_read_b64 v[116:117], v223 offset:24576
	ds_read_b64 v[118:119], v224 offset:24576
	v_exp_f32_e32 v122, v122
	v_exp_f32_e32 v123, v123
	v_bfe_i32 v231, v229, 16, 1
	v_and_b32_e32 v120, v120, v231
	v_bfe_i32 v232, v229, 17, 1
	v_and_b32_e32 v121, v121, v232
	v_add_f32_e32 v0, v120, v0
	v_add_f32_e32 v0, v121, v0
	s_waitcnt lgkmcnt(8)
	v_mfma_f32_32x32x16_bf16 v[32:47], v[236:239], v[208:211], v[32:47]
	ds_read_b64 v[8:9], v223 offset:28672
	ds_read_b64 v[10:11], v224 offset:28672
	v_exp_f32_e32 v124, v124
	v_exp_f32_e32 v125, v125
	v_bfe_i32 v231, v229, 18, 1
	v_and_b32_e32 v122, v122, v231
	v_bfe_i32 v232, v229, 19, 1
	v_and_b32_e32 v123, v123, v232
	v_add_f32_e32 v0, v122, v0
	v_add_f32_e32 v0, v123, v0
	s_waitcnt lgkmcnt(8)
	v_mfma_f32_32x32x16_bf16 v[48:63], v[240:243], v[208:211], v[48:63]
	ds_read_b64 v[12:13], v225 offset:16384
	ds_read_b64 v[14:15], v226 offset:16384
	v_exp_f32_e32 v126, v126
	v_exp_f32_e32 v127, v127
	v_bfe_i32 v231, v229, 24, 1
	v_and_b32_e32 v124, v124, v231
	v_bfe_i32 v232, v229, 25, 1
	v_and_b32_e32 v125, v125, v232
	v_add_f32_e32 v0, v124, v0
	v_add_f32_e32 v0, v125, v0
	v_bfe_i32 v231, v229, 26, 1
	v_and_b32_e32 v126, v126, v231
	v_bfe_i32 v232, v229, 27, 1
	v_and_b32_e32 v127, v127, v232
	v_add_f32_e32 v0, v126, v0
	v_add_f32_e32 v0, v127, v0
	v_cvt_pk_bf16_f32 v2, v120, v121
	v_cvt_pk_bf16_f32 v3, v122, v123
	v_cvt_pk_bf16_f32 v4, v124, v125
	v_cvt_pk_bf16_f32 v5, v126, v127
	s_nop 1
	ds_read_b64 v[236:237], v225 offset:20480
	ds_read_b64 v[238:239], v226 offset:20480
	s_waitcnt lgkmcnt(10)
	v_mfma_f32_32x32x16_bf16 v[80:95], v[244:247], v[2:5], v[80:95]
	ds_read_b64 v[240:241], v225 offset:24576
	ds_read_b64 v[242:243], v226 offset:24576
	v_exp_f32_e32 v96, v96
	v_exp_f32_e32 v97, v97
	s_waitcnt lgkmcnt(10)
	v_mfma_f32_32x32x16_bf16 v[64:79], v[112:115], v[2:5], v[64:79]
	ds_read_b64 v[120:121], v225 offset:28672
	ds_read_b64 v[122:123], v226 offset:28672
	v_exp_f32_e32 v98, v98
	v_exp_f32_e32 v99, v99
	v_bfe_i32 v231, v230, 0, 1
	v_and_b32_e32 v96, v96, v231
	v_bfe_i32 v232, v230, 1, 1
	v_and_b32_e32 v97, v97, v232
	v_add_f32_e32 v0, v96, v0
	v_add_f32_e32 v0, v97, v0
	s_waitcnt lgkmcnt(10)
	v_mfma_f32_32x32x16_bf16 v[48:63], v[116:119], v[2:5], v[48:63]
	ds_read_b64 v[124:125], v227 offset:16384
	ds_read_b64 v[126:127], v228 offset:16384
	v_exp_f32_e32 v100, v100
	v_exp_f32_e32 v101, v101
	v_bfe_i32 v231, v230, 2, 1
	v_and_b32_e32 v98, v98, v231
	v_bfe_i32 v232, v230, 3, 1
	v_and_b32_e32 v99, v99, v232
	v_add_f32_e32 v0, v98, v0
	v_add_f32_e32 v0, v99, v0
	s_waitcnt lgkmcnt(10)
	v_mfma_f32_32x32x16_bf16 v[32:47], v[8:11], v[2:5], v[32:47]
	ds_read_b64 v[244:245], v227 offset:20480
	ds_read_b64 v[246:247], v228 offset:20480
	v_exp_f32_e32 v102, v102
	v_exp_f32_e32 v103, v103
	v_bfe_i32 v231, v230, 8, 1
	v_and_b32_e32 v100, v100, v231
	v_bfe_i32 v232, v230, 9, 1
	v_and_b32_e32 v101, v101, v232
	v_add_f32_e32 v0, v100, v0
	v_add_f32_e32 v0, v101, v0
	v_bfe_i32 v231, v230, 10, 1
	v_and_b32_e32 v102, v102, v231
	v_bfe_i32 v232, v230, 11, 1
	v_and_b32_e32 v103, v103, v232
	v_add_f32_e32 v0, v102, v0
	v_add_f32_e32 v0, v103, v0
	v_cvt_pk_bf16_f32 v2, v96, v97
	v_cvt_pk_bf16_f32 v3, v98, v99
	v_cvt_pk_bf16_f32 v4, v100, v101
	v_cvt_pk_bf16_f32 v5, v102, v103
	s_nop 1
	ds_read_b64 v[112:113], v227 offset:24576
	ds_read_b64 v[114:115], v228 offset:24576
	s_waitcnt lgkmcnt(12)
	v_mfma_f32_32x32x16_bf16 v[80:95], v[12:15], v[2:5], v[80:95]
	ds_read_b64 v[116:117], v227 offset:28672
	ds_read_b64 v[118:119], v228 offset:28672
	v_exp_f32_e32 v104, v104
	v_exp_f32_e32 v105, v105
	s_waitcnt lgkmcnt(12)
	v_mfma_f32_32x32x16_bf16 v[64:79], v[236:239], v[2:5], v[64:79]
	v_exp_f32_e32 v106, v106
	v_exp_f32_e32 v107, v107
	v_bfe_i32 v231, v230, 16, 1
	v_and_b32_e32 v104, v104, v231
	v_bfe_i32 v232, v230, 17, 1
	v_and_b32_e32 v105, v105, v232
	v_add_f32_e32 v0, v104, v0
	v_add_f32_e32 v0, v105, v0
	s_waitcnt lgkmcnt(10)
	v_mfma_f32_32x32x16_bf16 v[48:63], v[240:243], v[2:5], v[48:63]
	v_exp_f32_e32 v108, v108
	v_exp_f32_e32 v109, v109
	v_bfe_i32 v231, v230, 18, 1
	v_and_b32_e32 v106, v106, v231
	v_bfe_i32 v232, v230, 19, 1
	v_and_b32_e32 v107, v107, v232
	v_add_f32_e32 v0, v106, v0
	v_add_f32_e32 v0, v107, v0
	s_waitcnt lgkmcnt(8)
	v_mfma_f32_32x32x16_bf16 v[32:47], v[120:123], v[2:5], v[32:47]
	v_exp_f32_e32 v110, v110
	v_exp_f32_e32 v111, v111
	v_bfe_i32 v231, v230, 24, 1
	v_and_b32_e32 v108, v108, v231
	v_bfe_i32 v232, v230, 25, 1
	v_and_b32_e32 v109, v109, v232
	v_add_f32_e32 v0, v108, v0
	v_add_f32_e32 v0, v109, v0
	v_bfe_i32 v231, v230, 26, 1
	v_and_b32_e32 v110, v110, v231
	v_bfe_i32 v232, v230, 27, 1
	v_and_b32_e32 v111, v111, v232
	v_add_f32_e32 v0, v110, v0
	v_add_f32_e32 v0, v111, v0
	v_cvt_pk_bf16_f32 v2, v104, v105
	v_cvt_pk_bf16_f32 v3, v106, v107
	v_cvt_pk_bf16_f32 v4, v108, v109
	v_cvt_pk_bf16_f32 v5, v110, v111
	s_nop 1
	s_waitcnt lgkmcnt(6)
	v_mfma_f32_32x32x16_bf16 v[80:95], v[124:127], v[2:5], v[80:95]
	s_waitcnt lgkmcnt(4)
	v_mfma_f32_32x32x16_bf16 v[64:79], v[244:247], v[2:5], v[64:79]
	s_waitcnt lgkmcnt(2)
	v_mfma_f32_32x32x16_bf16 v[48:63], v[112:115], v[2:5], v[48:63]
	s_waitcnt lgkmcnt(0)
	v_mfma_f32_32x32x16_bf16 v[32:47], v[116:119], v[2:5], v[32:47]
	v_add_f32_e32 v219, v219, v0
